# dilated attention: lane constants, LDS fragment addresses and band-edge masks computed once per workgroup instead of per item
# speedup vs baseline: 1.0032x; 1.0032x over previous
.LBB0_330:
	s_load_dwordx2 s[22:23], s[0:1], 0xb8
	s_load_dwordx2 s[24:25], s[0:1], 0xd0
	s_waitcnt vmcnt(0)
	v_xor_b32_e32 v66, 0x80000000, v1
	v_mov_b32_e32 v67, v66
	v_mov_b32_e32 v68, v66
	v_mov_b32_e32 v69, v66
	s_movk_i32 s41, 0x90
	s_mov_b32 s15, 0
	v_mov_b32_e32 v147, 0
	s_movk_i32 s42, 0xffe0
	s_movk_i32 s43, 0x1200
	s_mov_b32 s8, 0x3f803f80
	v_lshrrev_b32_e32 v15, 6, v0
	v_and_b32_e32 v16, 15, v0
	v_bfe_u32 v148, v0, 4, 2
	v_readfirstlane_b32 s92, v15
	v_lshl_or_b32 v17, v15, 5, v16
	v_lshlrev_b32_e32 v146, 2, v148
	v_sub_u32_e32 v14, v16, v146
	v_mov_b32_e32 v15, 0x90
	v_mul_u32_u24_e32 v194, v17, v15
	v_lshl_add_u32 v194, v148, 4, v194
	v_add_u32_e32 v194, 16, v194
	v_lshrrev_b32_e32 v195, 2, v16
	v_add_u32_e32 v195, v195, v146
	v_lshl_add_u32 v195, s92, 5, v195
	v_mul_u32_u24_e32 v195, v195, v15
	v_and_b32_e32 v16, 3, v0
	v_lshl_add_u32 v195, v16, 3, v195
	v_add_u32_e32 v195, 0xd810, v195
	v_cmp_le_i32_e64 s[76:77], v14, 0
	v_cmp_le_i32_e64 s[78:79], v14, 1
	v_cmp_le_i32_e64 s[80:81], v14, 2
	v_cmp_le_i32_e64 s[82:83], v14, 3
	v_cmp_ge_i32_e64 s[84:85], v14, 0
	v_cmp_ge_i32_e64 s[86:87], v14, 1
	v_cmp_ge_i32_e64 s[88:89], v14, 2
	v_cmp_ge_i32_e64 s[90:91], v14, 3
	v_mov_b32_e32 v10, 0x3f803f80
	v_mov_b32_e32 v11, v10
	v_mov_b32_e32 v12, v10
	v_mov_b32_e32 v13, v10
	s_branch .LBB0_332

.LBB0_361:
	ds_read_b128 v[178:181], v194 offset:0
	ds_read_b128 v[182:185], v194 offset:64
	ds_read_b128 v[186:189], v194 offset:2304
	ds_read_b128 v[190:193], v194 offset:2368
	ds_read_b64_tr_b16 v[200:201], v195 offset:0
	ds_read_b64_tr_b16 v[202:203], v195 offset:2304
	ds_read_b64_tr_b16 v[204:205], v195 offset:32
	ds_read_b64_tr_b16 v[206:207], v195 offset:2336
	ds_read_b64_tr_b16 v[208:209], v195 offset:64
	ds_read_b64_tr_b16 v[210:211], v195 offset:2368
	ds_read_b64_tr_b16 v[212:213], v195 offset:96
	ds_read_b64_tr_b16 v[214:215], v195 offset:2400
	v_lshrrev_b32_e32 v15, 3, v0
	v_and_b32_e32 v16, 7, v0
	v_lshlrev_b32_e32 v16, 4, v16
	v_mad_u32_u24 v196, v15, s95, v16
	v_and_b32_e32 v16, 48, v0
	v_mad_u32_u24 v198, v17, s95, v16
	s_lshl_b32 s60, s95, 6
	s_lshl_b32 s61, s95, 4
	s_sub_i32 s93, 4, s92
	s_max_i32 s93, s93, 0
	s_cmp_eq_u32 s17, 0
	s_cselect_b32 s93, 0, s93
	v_mov_b32_e32 v138, 0
	v_mov_b32_e32 v139, 0
	v_mov_b32_e32 v140, 0
	v_mov_b32_e32 v141, 0
	v_mov_b32_e32 v118, 0
	v_mov_b32_e32 v119, 0
	v_mov_b32_e32 v120, 0
	v_mov_b32_e32 v121, 0
	v_mov_b32_e32 v134, 0
	v_mov_b32_e32 v135, 0
	v_mov_b32_e32 v136, 0
	v_mov_b32_e32 v137, 0
	v_mov_b32_e32 v130, 0
	v_mov_b32_e32 v131, 0
	v_mov_b32_e32 v132, 0
	v_mov_b32_e32 v133, 0
	v_mov_b32_e32 v126, 0
	v_mov_b32_e32 v127, 0
	v_mov_b32_e32 v128, 0
	v_mov_b32_e32 v129, 0
	v_mov_b32_e32 v122, 0
	v_mov_b32_e32 v123, 0
	v_mov_b32_e32 v124, 0
	v_mov_b32_e32 v125, 0
	v_mov_b32_e32 v114, 0
	v_mov_b32_e32 v115, 0
	v_mov_b32_e32 v116, 0
	v_mov_b32_e32 v117, 0
	v_mov_b32_e32 v106, 0
	v_mov_b32_e32 v107, 0
	v_mov_b32_e32 v108, 0
	v_mov_b32_e32 v109, 0
	v_mov_b32_e32 v110, 0
	v_mov_b32_e32 v111, 0
	v_mov_b32_e32 v112, 0
	v_mov_b32_e32 v113, 0
	v_mov_b32_e32 v102, 0
	v_mov_b32_e32 v103, 0
	v_mov_b32_e32 v104, 0
	v_mov_b32_e32 v105, 0
	s_waitcnt lgkmcnt(8)
	v_mfma_f32_16x16x32_bf16 v[150:153], v[178:181], v[74:77], v[66:69]
	v_mfma_f32_16x16x32_bf16 v[154:157], v[186:189], v[74:77], v[66:69]
	v_mfma_f32_16x16x32_bf16 v[162:165], v[186:189], v[82:85], v[66:69]
	v_mfma_f32_16x16x32_bf16 v[150:153], v[182:185], v[70:73], v[150:153]
	v_mfma_f32_16x16x32_bf16 v[154:157], v[190:193], v[70:73], v[154:157]
	v_mfma_f32_16x16x32_bf16 v[162:165], v[190:193], v[78:81], v[162:165]
	s_waitcnt lgkmcnt(0)
	ds_read_b128 v[178:181], v194 offset:4608
	ds_read_b128 v[182:185], v194 offset:4672
	ds_read_b128 v[186:189], v194 offset:6912
	ds_read_b128 v[190:193], v194 offset:6976
	ds_read_b64_tr_b16 v[216:217], v195 offset:4608
	ds_read_b64_tr_b16 v[218:219], v195 offset:6912
	ds_read_b64_tr_b16 v[220:221], v195 offset:4640
	ds_read_b64_tr_b16 v[222:223], v195 offset:6944
	ds_read_b64_tr_b16 v[224:225], v195 offset:4672
	ds_read_b64_tr_b16 v[226:227], v195 offset:6976
	ds_read_b64_tr_b16 v[228:229], v195 offset:4704
	ds_read_b64_tr_b16 v[230:231], v195 offset:7008
